# r3: chunk-state loads issued right after the V-row loads (in-order vmcnt: V wait = vmcnt(8)), hiding their L2-miss latency behind V staging and the score step
# speedup vs baseline: 1.0025x; 1.0016x over previous
; #define LAS __attribute__((address_space(3)))
; __device__ __forceinline__ int seqidx(int b, int hl, int dir, int c) { return ((b * 8 + hl) * 2 + dir) * 64 + c; }
; __device__ __forceinline__ u32x4 pack8(const float (&v)[8]) { u32x4 w; w.x = cvt_pk_bf16(v[0], v[1]); w.y = cvt_pk_bf16(v[2], v[3]); w.z = cvt_pk_bf16(v[4], v[5]); w.w = cvt_pk_bf16(v[6], v[7]); return w; }
; __device__ __forceinline__ void r3_item(const Args& a, int L, int item, LAS unsigned char* lds) {
;     ...
;     { const int mat = tid >> 8, i = (tid >> 2) & 63, g = tid & 3;
;         const int col = mat == 0 ? (hl < 4 ? GQ + hl * 64 : RQ + (hl - 4) * 64) : (hl < 4 ? GK + hl * 64 : RK + (hl - 4) * 64);
;         float va[8], vb[8]; load_qk16(a, proj + (R0 + i) * LD + col, hl, c * 64 + i, g, va, vb);
;         const float sg = mat == 0 ? 1.f : -1.f;
; #pragma unroll
;         for (int dir = 0; dir < 2; ++dir) { float ta[8], tb[8];
; #pragma unroll
;             for (int e = 0; e < 8; ++e) { ta[e] = va[e] * __expf(sg * cum[(dir * 64 + i) * 64 + g * 8 + e]); tb[e] = vb[e] * __expf(sg * cum[(dir * 64 + i) * 64 + 32 + g * 8 + e]); }
;             LAS bf16_t* dst = QK + ((dir * 2 + mat) * 64 + i) * PT;
;             *(LAS u32x4*)(dst + g * 8) = pack8(ta); *(LAS u32x4*)(dst + 32 + g * 8) = pack8(tb); } }
;     { const int j = tid >> 3, vg = tid & 7; const int vcol = hl < 4 ? GV + hl * 128 : RV + (hl - 4) * 128;
;         const bf16_t* vp = proj + (R0 + j) * LD + vcol + vg * 16;
; #pragma unroll
;         for (int q = 0; q < 2; ++q) { const u32x4 w = *(const u32x4*)(vp + q * 8); const int v0 = vg * 16 + q * 8;
;             VT[(v0 + 0) * PT + j] = (bf16_t)(w.x & 0xffff); VT[(v0 + 1) * PT + j] = (bf16_t)(w.x >> 16); VT[(v0 + 2) * PT + j] = (bf16_t)(w.y & 0xffff); VT[(v0 + 3) * PT + j] = (bf16_t)(w.y >> 16);
;             VT[(v0 + 4) * PT + j] = (bf16_t)(w.z & 0xffff); VT[(v0 + 5) * PT + j] = (bf16_t)(w.z >> 16); VT[(v0 + 6) * PT + j] = (bf16_t)(w.w & 0xffff); VT[(v0 + 7) * PT + j] = (bf16_t)(w.w >> 16); } }
;     ...
;         bf16x8 stf[2][4];
; #pragma unroll
;         for (int dir = 0; dir < 2; ++dir) { const bf16_t* stp = (const bf16_t*)(a.ws + WS_ST) + (size_t)seqidx(b, hl, dir, c) * 8192 + (vt * 32 + r32) * 64 + hi * 8;
; #pragma unroll
;             for (int ks = 0; ks < 4; ++ks) stf[dir][ks] = *(const bf16x8*)(stp + ks * 16); }
.LBB0_116:
	v_lshlrev_b32_e32 v16, 8, v21
	v_lshlrev_b32_e32 v17, 2, v22
	v_add3_u32 v16, 0, v16, v17
	ds_read_b128 v[26:29], v16
	ds_read_b128 v[30:33], v16 offset:16
	ds_read_b128 v[34:37], v16 offset:128
	ds_read_b128 v[38:41], v16 offset:144
	v_lshrrev_b32_e32 v17, 2, v24
	s_mov_b32 s5, 0xfffffc0
	s_waitcnt lgkmcnt(3)
	v_mul_f32_e32 v22, v20, v26
	s_waitcnt lgkmcnt(1)
	v_mul_f32_e32 v26, v20, v35
	v_mul_f32_e32 v26, 0x3fb8aa3b, v26
	v_exp_f32_e32 v26, v26
	v_mul_f32_e32 v23, v20, v34
	v_mul_f32_e32 v25, v20, v27
	v_mul_f32_e32 v27, v20, v36
	v_mul_f32_e32 v34, v11, v26
	v_mul_f32_e32 v26, v20, v28
	v_mul_f32_e32 v28, v20, v29
	v_mul_f32_e32 v29, v20, v37
	v_mul_f32_e32 v26, 0x3fb8aa3b, v26
	v_mul_f32_e32 v27, 0x3fb8aa3b, v27
	v_mul_f32_e32 v28, 0x3fb8aa3b, v28
	v_mul_f32_e32 v29, 0x3fb8aa3b, v29
	v_exp_f32_e32 v26, v26
	v_exp_f32_e32 v27, v27
	v_exp_f32_e32 v28, v28
	v_exp_f32_e32 v29, v29
	v_mul_f32_e32 v35, v14, v26
	v_mul_f32_e32 v36, v8, v27
	v_mul_f32_e32 v27, v15, v28
	v_mul_f32_e32 v37, v9, v29
	v_mul_f32_e32 v26, v20, v30
	s_waitcnt lgkmcnt(0)
	v_mul_f32_e32 v28, v20, v38
	v_mul_f32_e32 v29, v20, v31
	v_mul_f32_e32 v26, 0x3fb8aa3b, v26
	v_mul_f32_e32 v28, 0x3fb8aa3b, v28
	v_mul_f32_e32 v29, 0x3fb8aa3b, v29
	v_exp_f32_e32 v26, v26
	v_exp_f32_e32 v28, v28
	v_exp_f32_e32 v29, v29
	v_mul_f32_e32 v22, 0x3fb8aa3b, v22
	v_mul_f32_e32 v31, v12, v26
	v_mul_f32_e32 v38, v2, v28
	v_mul_f32_e32 v28, v13, v29
	v_mul_f32_e32 v26, v20, v32
	v_mul_f32_e32 v29, v20, v40
	v_mul_f32_e32 v32, v20, v33
	v_mul_f32_e32 v29, 0x3fb8aa3b, v29
	v_mul_f32_e32 v32, 0x3fb8aa3b, v32
	v_mul_f32_e32 v25, 0x3fb8aa3b, v25
	v_mul_f32_e32 v30, v20, v39
	v_mul_f32_e32 v26, 0x3fb8aa3b, v26
	v_exp_f32_e32 v29, v29
	v_exp_f32_e32 v32, v32
	v_mul_f32_e32 v33, v20, v41
	v_exp_f32_e32 v22, v22
	v_mul_f32_e32 v23, 0x3fb8aa3b, v23
	v_exp_f32_e32 v25, v25
	v_mul_f32_e32 v30, 0x3fb8aa3b, v30
	v_exp_f32_e32 v26, v26
	v_mul_f32_e32 v33, 0x3fb8aa3b, v33
	v_exp_f32_e32 v23, v23
	v_exp_f32_e32 v30, v30
	v_exp_f32_e32 v33, v33
	v_and_or_b32 v21, v17, s5, v21
	v_mul_f32_e32 v40, v6, v29
	v_mul_f32_e32 v29, v5, v32
	v_mul_lo_u32 v21, v21, s81
	v_mul_f32_e32 v22, v18, v22
	v_mul_f32_e32 v25, v19, v25
	v_mul_f32_e32 v39, v4, v26
	v_cvt_pk_bf16_f32 v26, v22, v25
	v_cvt_pk_bf16_f32 v27, v35, v27
	v_cvt_pk_bf16_f32 v28, v31, v28
	v_cvt_pk_bf16_f32 v29, v39, v29
	v_add3_u32 v0, 0, v21, v0
	v_mul_f32_e32 v23, v10, v23
	v_mul_f32_e32 v30, v3, v30
	v_mul_f32_e32 v32, v7, v33
	ds_write_b128 v0, v[26:29] offset:51200
	v_cvt_pk_bf16_f32 v26, v23, v34
	v_cvt_pk_bf16_f32 v27, v36, v37
	v_cvt_pk_bf16_f32 v28, v38, v30
	v_cvt_pk_bf16_f32 v29, v40, v32
	ds_write_b128 v0, v[26:29] offset:51264
	ds_read_b128 v[26:29], v16 offset:16384
	ds_read_b128 v[30:33], v16 offset:16400
	ds_read_b128 v[34:37], v16 offset:16512
	ds_read_b128 v[38:41], v16 offset:16528
	v_add_u32_e32 v0, 0xc800, v0
	s_lshl_b32 s5, s28, 7
	s_waitcnt lgkmcnt(3)
	v_mul_f32_e32 v21, v20, v26
	s_waitcnt lgkmcnt(1)
	v_mul_f32_e32 v16, v20, v34
	v_mul_f32_e32 v22, v20, v27
	v_mul_f32_e32 v23, v20, v35
	v_mul_f32_e32 v21, 0x3fb8aa3b, v21
	v_mul_f32_e32 v16, 0x3fb8aa3b, v16
	v_mul_f32_e32 v22, 0x3fb8aa3b, v22
	v_mul_f32_e32 v23, 0x3fb8aa3b, v23
	v_exp_f32_e32 v21, v21
	v_exp_f32_e32 v16, v16
	v_exp_f32_e32 v22, v22
	v_exp_f32_e32 v23, v23
	v_mul_f32_e32 v18, v18, v21
	v_mul_f32_e32 v10, v10, v16
	v_mul_f32_e32 v16, v19, v22
	v_mul_f32_e32 v11, v11, v23
	v_mul_f32_e32 v19, v20, v28
	v_mul_f32_e32 v21, v20, v36
	v_mul_f32_e32 v22, v20, v29
	v_mul_f32_e32 v23, v20, v37
	v_mul_f32_e32 v19, 0x3fb8aa3b, v19
	v_mul_f32_e32 v21, 0x3fb8aa3b, v21
	v_mul_f32_e32 v22, 0x3fb8aa3b, v22
	v_mul_f32_e32 v23, 0x3fb8aa3b, v23
	v_exp_f32_e32 v19, v19
	v_exp_f32_e32 v21, v21
	v_exp_f32_e32 v22, v22
	v_exp_f32_e32 v23, v23
	v_mul_f32_e32 v14, v14, v19
	v_mul_f32_e32 v8, v8, v21
	v_mul_f32_e32 v15, v15, v22
	v_mul_f32_e32 v9, v9, v23
	v_mul_f32_e32 v19, v20, v30
	s_waitcnt lgkmcnt(0)
	v_mul_f32_e32 v21, v20, v38
	v_mul_f32_e32 v22, v20, v31
	v_mul_f32_e32 v23, v20, v39
	v_mul_f32_e32 v19, 0x3fb8aa3b, v19
	v_mul_f32_e32 v21, 0x3fb8aa3b, v21
	v_mul_f32_e32 v22, 0x3fb8aa3b, v22
	v_mul_f32_e32 v23, 0x3fb8aa3b, v23
	v_exp_f32_e32 v19, v19
	v_exp_f32_e32 v21, v21
	v_exp_f32_e32 v22, v22
	v_exp_f32_e32 v23, v23
	v_mul_f32_e32 v12, v12, v19
	v_mul_f32_e32 v19, v2, v21
	v_mul_f32_e32 v13, v13, v22
	v_mul_f32_e32 v21, v3, v23
	v_mul_f32_e32 v2, v20, v32
	v_mul_f32_e32 v3, v20, v40
	v_mul_f32_e32 v22, v20, v33
	v_mul_f32_e32 v20, v20, v41
	v_mul_f32_e32 v2, 0x3fb8aa3b, v2
	v_mul_f32_e32 v3, 0x3fb8aa3b, v3
	v_mul_f32_e32 v22, 0x3fb8aa3b, v22
	v_mul_f32_e32 v20, 0x3fb8aa3b, v20
	v_exp_f32_e32 v2, v2
	v_exp_f32_e32 v3, v3
	v_exp_f32_e32 v22, v22
	v_exp_f32_e32 v20, v20
	v_mul_f32_e32 v23, v4, v2
	v_mul_f32_e32 v6, v6, v3
	v_mul_f32_e32 v5, v5, v22
	v_mul_f32_e32 v7, v7, v20
	v_cvt_pk_bf16_f32 v2, v18, v16
	v_cvt_pk_bf16_f32 v3, v14, v15
	v_cvt_pk_bf16_f32 v4, v12, v13
	v_ashrrev_i32_e32 v20, 3, v24
	v_cvt_pk_bf16_f32 v5, v23, v5
	ds_write_b128 v0, v[2:5] offset:18432
	v_cvt_pk_bf16_f32 v2, v10, v11
	v_cvt_pk_bf16_f32 v3, v8, v9
	v_cvt_pk_bf16_f32 v4, v19, v21
	v_ashrrev_i32_e32 v21, 31, v20
	v_cvt_pk_bf16_f32 v5, v6, v7
	ds_write_b128 v0, v[2:5] offset:18496
	v_lshl_add_u64 v[18:19], s[0:1], 0, v[20:21]
	v_mov_b64_e32 v[2:3], s[22:23]
	s_or_b32 s7, s5, 0xe00
	s_add_i32 s24, s5, 0x1200
	v_mad_u64_u32 v[22:23], s[0:1], v18, s79, v[2:3]
	s_and_b64 s[10:11], s[2:3], exec
	v_mov_b32_e32 v0, v23
	s_cselect_b32 s7, s7, s24
	v_mad_u64_u32 v[2:3], s[0:1], v19, s79, v[0:1]
	v_lshlrev_b32_e32 v0, 4, v24
	v_mov_b32_e32 v23, v2
	s_lshl_b32 s24, s7, 1
	v_and_b32_e32 v21, 0x70, v0
	v_lshl_add_u64 v[2:3], v[22:23], 0, s[24:25]
	v_lshlrev_b32_e32 v0, 1, v21
	v_lshl_add_u64 v[6:7], v[2:3], 0, v[0:1]
	global_load_dwordx4 v[2:5], v[6:7], off
	global_load_dwordx4 v[112:115], v[6:7], off offset:16
	v_and_b32_e32 v106, 31, v24
	v_bfe_u32 v107, v24, 5, 1
	v_lshlrev_b32_e32 v106, 7, v106
	v_lshl_or_b32 v106, v107, 4, v106
	v_bfe_u32 v107, v24, 6, 2
	s_lshr_b32 s100, s15, 6
	s_lshl_b32 s100, s100, 7
	s_and_b32 s101, s15, 63
	s_or_b32 s100, s100, s101
	v_lshl_or_b32 v106, v107, 12, v106
	s_lshl_b32 s100, s100, 14
	s_add_u32 s100, s8, s100
	s_addc_u32 s101, s9, 0
	global_load_dwordx4 v[72:75], v106, s[100:101]
	global_load_dwordx4 v[76:79], v106, s[100:101] offset:32
	global_load_dwordx4 v[80:83], v106, s[100:101] offset:64
	global_load_dwordx4 v[84:87], v106, s[100:101] offset:96
	s_add_u32 s100, s100, 0x100000
	s_addc_u32 s101, s101, 0
	global_load_dwordx4 v[88:91], v106, s[100:101]
	global_load_dwordx4 v[92:95], v106, s[100:101] offset:32
	global_load_dwordx4 v[96:99], v106, s[100:101] offset:64
	global_load_dwordx4 v[100:103], v106, s[100:101] offset:96
	v_mul_u32_u24_e32 v8, 0x90, v21
	v_lshlrev_b32_e32 v9, 1, v20
	v_add3_u32 v8, 0, v8, v9
	s_waitcnt vmcnt(8) lgkmcnt(0)
; #define LAS __attribute__((address_space(3)))
; __device__ __forceinline__ unsigned cvt_pk_bf16(float lo, float hi) { unsigned r; asm volatile("v_cvt_pk_bf16_f32 %0, %1, %2" : "=v"(r) : "v"(lo), "v"(hi)); return r; }
; __device__ __forceinline__ void r3_item(const Args& a, int L, int item, LAS unsigned char* lds) {
;     ...
;     { const int j = tid >> 3, vg = tid & 7; const int vcol = hl < 4 ? GV + hl * 128 : RV + (hl - 4) * 128;
;         const bf16_t* vp = proj + (R0 + j) * LD + vcol + vg * 16;
; #pragma unroll
;         for (int q = 0; q < 2; ++q) { const u32x4 w = *(const u32x4*)(vp + q * 8); const int v0 = vg * 16 + q * 8;
;             VT[(v0 + 0) * PT + j] = (bf16_t)(w.x & 0xffff); VT[(v0 + 1) * PT + j] = (bf16_t)(w.x >> 16); VT[(v0 + 2) * PT + j] = (bf16_t)(w.y & 0xffff); VT[(v0 + 3) * PT + j] = (bf16_t)(w.y >> 16);
;             VT[(v0 + 4) * PT + j] = (bf16_t)(w.z & 0xffff); VT[(v0 + 5) * PT + j] = (bf16_t)(w.z >> 16); VT[(v0 + 6) * PT + j] = (bf16_t)(w.w & 0xffff); VT[(v0 + 7) * PT + j] = (bf16_t)(w.w >> 16); } }
;     __syncthreads();
;     { const int dir = wid >> 2, it = (wid >> 1) & 1, jt = wid & 1; f32x16 sc = f32x16{};
;         const LAS bf16_t* Qt = QK + ((dir * 2 + 0) * 64) * PT; const LAS bf16_t* Kt = QK + ((dir * 2 + 1) * 64) * PT;
; #pragma unroll
;         for (int ks = 0; ks < 4; ++ks) { const bf16x8 av = *(const LAS bf16x8*)(Kt + (jt * 32 + r32) * PT + ks * 16 + hi * 8), bv = *(const LAS bf16x8*)(Qt + (it * 32 + r32) * PT + ks * 16 + hi * 8);
;             sc = __builtin_amdgcn_mfma_f32_32x32x16_bf16(av, bv, sc, 0, 0, 0); }
;         const int i = it * 32 + r32;
; #pragma unroll
;         for (int g4 = 0; g4 < 4; ++g4) { float v[4];
; #pragma unroll
;             for (int e = 0; e < 4; ++e) { const int j = jt * 32 + 8 * g4 + 4 * hi + e; const bool keep = dir == 0 ? (j <= i) : (j >= i); v[e] = keep ? sc[g4 * 4 + e] : 0.f; }
;             u32x2 w; w.x = cvt_pk_bf16(v[0], v[1]); w.y = cvt_pk_bf16(v[2], v[3]);
;             *(LAS u32x2*)(P + (dir * 64 + i) * PT + jt * 32 + 8 * g4 + 4 * hi) = w; } }
	ds_write_b16 v8, v2 offset:32768
	ds_write_b16_d16_hi v8, v2 offset:32912
	ds_write_b16 v8, v3 offset:33056
	ds_write_b16_d16_hi v8, v3 offset:33200
	ds_write_b16 v8, v4 offset:33344
	ds_write_b16_d16_hi v8, v4 offset:33488
	ds_write_b16 v8, v5 offset:33632
	ds_write_b16_d16_hi v8, v5 offset:33776
	v_ashrrev_i32_e32 v42, 6, v24
	v_and_b32_e32 v44, 1, v42
	v_and_b32_e32 v66, 31, v24
	v_lshlrev_b32_e32 v45, 5, v44
	v_bfe_u32 v25, v24, 5, 1
	ds_write_b16 v8, v112 offset:33920
	ds_write_b16_d16_hi v8, v112 offset:34064
	ds_write_b16 v8, v113 offset:34208
	ds_write_b16_d16_hi v8, v113 offset:34352
	ds_write_b16 v8, v114 offset:34496
	ds_write_b16_d16_hi v8, v114 offset:34640
	ds_write_b16 v8, v115 offset:34784
	ds_write_b16_d16_hi v8, v115 offset:34928
	v_ashrrev_i32_e32 v43, 8, v24
	s_movk_i32 s0, 0x4800
	v_or_b32_e32 v2, v45, v66
	v_mad_i32_i24 v6, v43, s0, 0
	v_mul_u32_u24_e32 v2, 0x90, v2
	v_lshlrev_b32_e32 v24, 4, v25
	v_add3_u32 v34, v6, v2, v24
	s_waitcnt lgkmcnt(0)
	s_barrier
	ds_read_b128 v[2:5], v34 offset:60416
	v_and_or_b32 v46, v17, 32, v66
	v_mul_u32_u24_e32 v7, 0x90, v46
	v_add3_u32 v38, v6, v7, v24
	ds_read_b128 v[6:9], v38 offset:51200
	ds_read_b128 v[26:29], v34 offset:60448
	ds_read_b128 v[30:33], v38 offset:51232
	s_waitcnt lgkmcnt(2)
	v_mfma_f32_32x32x16_bf16 v[2:17], v[2:5], v[6:9], 0
	v_lshlrev_b32_e32 v67, 2, v25
	v_readlane_b32 s7, v253, 24
	v_and_b32_e32 v68, 3, v42
	s_lshl_b32 s0, s4, 10
	s_or_b32 s0, s5, s0
	v_lshlrev_b32_e32 v69, 5, v43
	s_or_b32 s0, s0, s6
	s_waitcnt lgkmcnt(0)
	v_mfma_f32_32x32x16_bf16 v[2:17], v[26:29], v[30:33], v[2:17]
	ds_read_b128 v[26:29], v34 offset:60480
	ds_read_b128 v[30:33], v38 offset:51264
	ds_read_b128 v[34:37], v34 offset:60512
	ds_read_b128 v[38:41], v38 offset:51296
	s_ashr_i32 s1, s0, 31
	s_movk_i32 s4, 0x210
	s_waitcnt lgkmcnt(2)
	v_mfma_f32_32x32x16_bf16 v[2:17], v[26:29], v[30:33], v[2:17]
	v_lshl_or_b32 v27, v43, 6, v46
	v_lshlrev_b32_e32 v26, 3, v25
	v_or_b32_e32 v25, v45, v67
	v_mul_lo_u32 v27, v27, s81
	v_add_u32_e32 v27, s7, v27
	v_lshlrev_b32_e32 v28, 6, v44
	v_cmp_le_u32_e32 vcc, v25, v46
	s_waitcnt lgkmcnt(0)
	v_mfma_f32_32x32x16_bf16 v[2:17], v[34:37], v[38:41], v[2:17]
	v_add3_u32 v26, v27, v28, v26
	v_cndmask_b32_e64 v27, 0, 1, vcc
	v_cmp_ge_u32_e32 vcc, v25, v46
	s_nop 1
	v_cndmask_b32_e64 v28, 0, 1, vcc
	v_cndmask_b32_e64 v27, v28, v27, s[38:39]
	v_and_b32_e32 v27, 1, v27
	v_cmp_eq_u32_e32 vcc, 1, v27
	v_or_b32_e32 v27, 1, v25
	s_nop 1
	v_cndmask_b32_e32 v2, 0, v2, vcc
	v_cmp_lt_u32_e32 vcc, v25, v46
	s_nop 1
	v_cndmask_b32_e64 v28, 0, 1, vcc
	v_cmp_ge_u32_e32 vcc, v27, v46
	s_nop 1
	v_cndmask_b32_e64 v27, 0, 1, vcc
	v_cndmask_b32_e64 v27, v27, v28, s[38:39]
	v_and_b32_e32 v27, 1, v27
	v_cmp_eq_u32_e32 vcc, 1, v27
	v_or_b32_e32 v27, 2, v25
	s_nop 0
	v_cndmask_b32_e32 v3, 0, v3, vcc
	v_cmp_le_u32_e32 vcc, v27, v46
	v_cvt_pk_bf16_f32 v2, v2, v3
	s_nop 1
	v_cndmask_b32_e64 v28, 0, 1, vcc
	v_cmp_ge_u32_e32 vcc, v27, v46
	s_nop 1
	v_cndmask_b32_e64 v27, 0, 1, vcc
	v_cndmask_b32_e64 v27, v27, v28, s[38:39]
	v_and_b32_e32 v27, 1, v27
	v_cmp_eq_u32_e32 vcc, 1, v27
	v_or_b32_e32 v27, 3, v25
	s_nop 0
	v_cndmask_b32_e32 v4, 0, v4, vcc
	v_cmp_le_u32_e32 vcc, v27, v46
	s_nop 1
	v_cndmask_b32_e64 v28, 0, 1, vcc
	v_cmp_ge_u32_e32 vcc, v27, v46
	s_nop 1
	v_cndmask_b32_e64 v27, 0, 1, vcc
	v_cndmask_b32_e64 v27, v27, v28, s[38:39]
	v_and_b32_e32 v27, 1, v27
	v_cmp_eq_u32_e32 vcc, 1, v27
	s_nop 1
	v_cndmask_b32_e32 v5, 0, v5, vcc
	v_cvt_pk_bf16_f32 v3, v4, v5
	ds_write_b64 v26, v[2:3]
	v_or_b32_e32 v2, 8, v25
	v_cmp_le_u32_e32 vcc, v2, v46
	s_nop 1
	v_cndmask_b32_e64 v3, 0, 1, vcc
	v_cmp_ge_u32_e32 vcc, v2, v46
	s_nop 1
	v_cndmask_b32_e64 v2, 0, 1, vcc
	v_cndmask_b32_e64 v2, v2, v3, s[38:39]
	v_and_b32_e32 v2, 1, v2
	v_cmp_eq_u32_e32 vcc, 1, v2
	v_or_b32_e32 v3, 9, v25
	s_nop 0
	v_cndmask_b32_e32 v2, 0, v6, vcc
	v_cmp_le_u32_e32 vcc, v3, v46
	s_nop 1
	v_cndmask_b32_e64 v4, 0, 1, vcc
	v_cmp_ge_u32_e32 vcc, v3, v46
	s_nop 1
	v_cndmask_b32_e64 v3, 0, 1, vcc
	v_cndmask_b32_e64 v3, v3, v4, s[38:39]
	v_and_b32_e32 v3, 1, v3
	v_cmp_eq_u32_e32 vcc, 1, v3
	v_or_b32_e32 v4, 10, v25
	s_nop 0
	v_cndmask_b32_e32 v3, 0, v7, vcc
	v_cmp_le_u32_e32 vcc, v4, v46
	v_cvt_pk_bf16_f32 v2, v2, v3
	s_nop 1
	v_cndmask_b32_e64 v5, 0, 1, vcc
	v_cmp_ge_u32_e32 vcc, v4, v46
	s_nop 1
	v_cndmask_b32_e64 v4, 0, 1, vcc
	v_cndmask_b32_e64 v4, v4, v5, s[38:39]
	v_and_b32_e32 v4, 1, v4
	v_cmp_eq_u32_e32 vcc, 1, v4
	v_or_b32_e32 v5, 11, v25
	s_nop 0
	v_cndmask_b32_e32 v4, 0, v8, vcc
	v_cmp_le_u32_e32 vcc, v5, v46
	s_nop 1
	v_cndmask_b32_e64 v6, 0, 1, vcc
	v_cmp_ge_u32_e32 vcc, v5, v46
	s_nop 1
	v_cndmask_b32_e64 v5, 0, 1, vcc
	v_cndmask_b32_e64 v5, v5, v6, s[38:39]
	v_and_b32_e32 v5, 1, v5
	v_cmp_eq_u32_e32 vcc, 1, v5
	s_nop 1
	v_cndmask_b32_e32 v5, 0, v9, vcc
	v_cvt_pk_bf16_f32 v3, v4, v5
	ds_write_b64 v26, v[2:3] offset:16
	v_or_b32_e32 v2, 16, v25
	v_cmp_le_u32_e32 vcc, v2, v46
	s_nop 1
	v_cndmask_b32_e64 v3, 0, 1, vcc
	v_cmp_ge_u32_e32 vcc, v2, v46
	s_nop 1
	v_cndmask_b32_e64 v2, 0, 1, vcc
	v_cndmask_b32_e64 v2, v2, v3, s[38:39]
	v_and_b32_e32 v2, 1, v2
	v_cmp_eq_u32_e32 vcc, 1, v2
	v_or_b32_e32 v3, 17, v25
	s_nop 0
	v_cndmask_b32_e32 v2, 0, v10, vcc
	v_cmp_le_u32_e32 vcc, v3, v46
	s_nop 1
	v_cndmask_b32_e64 v4, 0, 1, vcc
	v_cmp_ge_u32_e32 vcc, v3, v46
	s_nop 1
	v_cndmask_b32_e64 v3, 0, 1, vcc
	v_cndmask_b32_e64 v3, v3, v4, s[38:39]
	v_and_b32_e32 v3, 1, v3
	v_cmp_eq_u32_e32 vcc, 1, v3
	v_or_b32_e32 v4, 18, v25
	s_nop 0
	v_cndmask_b32_e32 v3, 0, v11, vcc
	v_cmp_le_u32_e32 vcc, v4, v46
	v_cvt_pk_bf16_f32 v2, v2, v3
	s_nop 1
	v_cndmask_b32_e64 v5, 0, 1, vcc
	v_cmp_ge_u32_e32 vcc, v4, v46
	s_nop 1
; #define LAS __attribute__((address_space(3)))
; __device__ __forceinline__ unsigned cvt_pk_bf16(float lo, float hi) { unsigned r; asm volatile("v_cvt_pk_bf16_f32 %0, %1, %2" : "=v"(r) : "v"(lo), "v"(hi)); return r; }
; __device__ __forceinline__ int crow(int r, int hi) { return (r & 3) + 8 * (r >> 2) + 4 * hi; }
; __device__ __forceinline__ int crow(int r, int hi) { return (r & 3) + 8 * (r >> 2) + 4 * hi; }
; __device__ __forceinline__ int seqidx(int b, int hl, int dir, int c) { return ((b * 8 + hl) * 2 + dir) * 64 + c; }
; __device__ __forceinline__ void r3_item(const Args& a, int L, int item, LAS unsigned char* lds) {
;     ...
;         for (int g4 = 0; g4 < 4; ++g4) { float v[4];
; #pragma unroll
;             for (int e = 0; e < 4; ++e) { const int j = jt * 32 + 8 * g4 + 4 * hi + e; const bool keep = dir == 0 ? (j <= i) : (j >= i); v[e] = keep ? sc[g4 * 4 + e] : 0.f; }
;             u32x2 w; w.x = cvt_pk_bf16(v[0], v[1]); w.y = cvt_pk_bf16(v[2], v[3]);
;             *(LAS u32x2*)(P + (dir * 64 + i) * PT + jt * 32 + 8 * g4 + 4 * hi) = w; } }
;     __syncthreads();
;     { const int it = wid >> 2, vt = wid & 3; f32x16 acc = f32x16{};
;         bf16x8 stf[2][4];
; #pragma unroll
;         for (int dir = 0; dir < 2; ++dir) { const bf16_t* stp = (const bf16_t*)(a.ws + WS_ST) + (size_t)seqidx(b, hl, dir, c) * 8192 + (vt * 32 + r32) * 64 + hi * 8;
; #pragma unroll
;             for (int ks = 0; ks < 4; ++ks) stf[dir][ks] = *(const bf16x8*)(stp + ks * 16); }
; #pragma unroll
;         for (int dir = 0; dir < 2; ++dir) { const LAS bf16_t* Qt = QK + ((dir * 2 + 0) * 64) * PT;
; #pragma unroll
;             for (int ks = 0; ks < 4; ++ks) { const bf16x8 av = *(const LAS bf16x8*)(P + (dir * 64 + it * 32 + r32) * PT + ks * 16 + hi * 8), bv = *(const LAS bf16x8*)(VT + (vt * 32 + r32) * PT + ks * 16 + hi * 8);
;                 acc = __builtin_amdgcn_mfma_f32_32x32x16_bf16(av, bv, acc, 0, 0, 0); }
; #pragma unroll
;             for (int ks = 0; ks < 4; ++ks) { const bf16x8 av = *(const LAS bf16x8*)(Qt + (it * 32 + r32) * PT + ks * 16 + hi * 8), bv = stf[dir][ks];
;                 acc = __builtin_amdgcn_mfma_f32_32x32x16_bf16(av, bv, acc, 0, 0, 0); } }
;         __syncthreads();
;         LAS float* OL = (LAS float*)(lds + L_OL);
; #pragma unroll
;         for (int r = 0; r < 16; ++r) OL[(it * 32 + crow(r, hi)) * OLP + vt * 32 + r32] = acc[r]; }
	v_cndmask_b32_e64 v4, 0, 1, vcc
	v_cndmask_b32_e64 v4, v4, v5, s[38:39]
	v_and_b32_e32 v4, 1, v4
	v_cmp_eq_u32_e32 vcc, 1, v4
	v_or_b32_e32 v5, 19, v25
	s_nop 0
	v_cndmask_b32_e32 v4, 0, v12, vcc
	v_cmp_le_u32_e32 vcc, v5, v46
	s_nop 1
	v_cndmask_b32_e64 v6, 0, 1, vcc
	v_cmp_ge_u32_e32 vcc, v5, v46
	s_nop 1
	v_cndmask_b32_e64 v5, 0, 1, vcc
	v_cndmask_b32_e64 v5, v5, v6, s[38:39]
	v_and_b32_e32 v5, 1, v5
	v_cmp_eq_u32_e32 vcc, 1, v5
	s_nop 1
	v_cndmask_b32_e32 v5, 0, v13, vcc
	v_cvt_pk_bf16_f32 v3, v4, v5
	ds_write_b64 v26, v[2:3] offset:32
	v_or_b32_e32 v2, 24, v25
	v_cmp_le_u32_e32 vcc, v2, v46
	s_nop 1
	v_cndmask_b32_e64 v3, 0, 1, vcc
	v_cmp_ge_u32_e32 vcc, v2, v46
	s_nop 1
	v_cndmask_b32_e64 v2, 0, 1, vcc
	v_cndmask_b32_e64 v2, v2, v3, s[38:39]
	v_and_b32_e32 v2, 1, v2
	v_cmp_eq_u32_e32 vcc, 1, v2
	v_or_b32_e32 v3, 25, v25
	s_nop 0
	v_cndmask_b32_e32 v2, 0, v14, vcc
	v_cmp_le_u32_e32 vcc, v3, v46
	s_nop 1
	v_cndmask_b32_e64 v4, 0, 1, vcc
	v_cmp_ge_u32_e32 vcc, v3, v46
	s_nop 1
	v_cndmask_b32_e64 v3, 0, 1, vcc
	v_cndmask_b32_e64 v3, v3, v4, s[38:39]
	v_and_b32_e32 v3, 1, v3
	v_cmp_eq_u32_e32 vcc, 1, v3
	v_or_b32_e32 v4, 26, v25
	s_nop 0
	v_cndmask_b32_e32 v3, 0, v15, vcc
	v_cmp_le_u32_e32 vcc, v4, v46
	v_cvt_pk_bf16_f32 v2, v2, v3
	s_nop 1
	v_cndmask_b32_e64 v5, 0, 1, vcc
	v_cmp_ge_u32_e32 vcc, v4, v46
	s_nop 1
	v_cndmask_b32_e64 v4, 0, 1, vcc
	v_cndmask_b32_e64 v4, v4, v5, s[38:39]
	v_and_b32_e32 v4, 1, v4
	v_cmp_eq_u32_e32 vcc, 1, v4
	v_or_b32_e32 v5, 27, v25
	v_mov_b32_e32 v25, v1
	v_cndmask_b32_e32 v4, 0, v16, vcc
	v_cmp_le_u32_e32 vcc, v5, v46
	s_nop 1
	v_cndmask_b32_e64 v6, 0, 1, vcc
	v_cmp_ge_u32_e32 vcc, v5, v46
	s_nop 1
	v_cndmask_b32_e64 v5, 0, 1, vcc
	v_cndmask_b32_e64 v5, v5, v6, s[38:39]
	v_and_b32_e32 v5, 1, v5
	v_cmp_eq_u32_e32 vcc, 1, v5
	v_lshl_or_b32 v6, v68, 5, v66
	v_mul_u32_u24_e32 v6, 0x90, v6
	v_cndmask_b32_e32 v5, 0, v17, vcc
	v_cvt_pk_bf16_f32 v3, v4, v5
	ds_write_b64 v26, v[2:3] offset:48
	v_lshlrev_b32_e32 v2, 7, v66
	v_lshl_or_b32 v2, v68, 12, v2
	v_mov_b32_e32 v3, v1
	v_lshl_add_u64 v[2:3], s[8:9], 0, v[2:3]
	v_lshl_add_u64 v[62:63], v[2:3], 0, v[24:25]
	v_or_b32_e32 v2, v69, v66
	v_mul_lo_u32 v25, v2, s81
	v_add3_u32 v70, s7, v24, v25
	s_lshl_b64 s[6:7], s[0:1], 14
	v_add3_u32 v50, 0, v6, v24
	v_lshl_add_u64 v[64:65], v[62:63], 0, s[6:7]
	s_waitcnt lgkmcnt(0)
	s_barrier
	ds_read_b128 v[2:5], v70
	ds_read_b128 v[26:29], v50 offset:32768
	ds_read_b128 v[30:33], v70 offset:32
	ds_read_b128 v[34:37], v50 offset:32800
	s_waitcnt lgkmcnt(0)
	v_mfma_f32_32x32x16_bf16 v[2:17], v[2:5], v[26:29], 0
	v_add3_u32 v71, 0, v25, v24
	s_or_b32 s0, s0, 64
	s_ashr_i32 s1, s0, 31
	s_lshl_b64 s[0:1], s[0:1], 14
	v_mfma_f32_32x32x16_bf16 v[2:17], v[30:33], v[34:37], v[2:17]
	ds_read_b128 v[30:33], v70 offset:64
	ds_read_b128 v[42:45], v50 offset:32832
	ds_read_b128 v[46:49], v70 offset:96
	ds_read_b128 v[50:53], v50 offset:32864
	ds_read_b128 v[54:57], v71 offset:51200
	ds_read_b128 v[58:61], v71 offset:51232
	s_waitcnt lgkmcnt(0)
	v_mfma_f32_32x32x16_bf16 v[2:17], v[30:33], v[42:45], v[2:17]
	v_mfma_f32_32x32x16_bf16 v[2:17], v[46:49], v[50:53], v[2:17]
	s_waitcnt vmcnt(0)
	v_mfma_f32_32x32x16_bf16 v[2:17], v[54:57], v[72:75], v[2:17]
	s_waitcnt lgkmcnt(0)
	v_mfma_f32_32x32x16_bf16 v[2:17], v[58:61], v[76:79], v[2:17]
	ds_read_b128 v[30:33], v71 offset:51264
	ds_read_b128 v[54:57], v71 offset:51296
	s_waitcnt lgkmcnt(0)
	v_mfma_f32_32x32x16_bf16 v[2:17], v[30:33], v[80:83], v[2:17]
	ds_read_b128 v[30:33], v70 offset:9216
	v_lshl_add_u64 v[46:47], v[62:63], 0, s[0:1]
	s_and_b64 s[0:1], s[2:3], exec
	s_movk_i32 s0, 0x1400
	s_cselect_b32 s0, 0x1000, s0
	s_or_b32 s0, s0, s5
	s_waitcnt vmcnt(0)
	v_mfma_f32_32x32x16_bf16 v[2:17], v[54:57], v[84:87], v[2:17]
	ds_read_b128 v[38:41], v70 offset:9248
	s_waitcnt lgkmcnt(1)
	v_mfma_f32_32x32x16_bf16 v[2:17], v[30:33], v[26:29], v[2:17]
	s_waitcnt lgkmcnt(0)
	v_mfma_f32_32x32x16_bf16 v[2:17], v[38:41], v[34:37], v[2:17]
	ds_read_b128 v[28:31], v70 offset:9280
	ds_read_b128 v[32:35], v70 offset:9312
	s_waitcnt lgkmcnt(0)
	v_mfma_f32_32x32x16_bf16 v[2:17], v[28:31], v[42:45], v[2:17]
	v_add_u32_e32 v44, 0xc800, v71
	ds_read_b128 v[36:39], v44 offset:18432
	ds_read_b128 v[40:43], v44 offset:18464
	v_mfma_f32_32x32x16_bf16 v[2:17], v[32:35], v[50:53], v[2:17]
	s_waitcnt vmcnt(0) lgkmcnt(0)
	v_mfma_f32_32x32x16_bf16 v[2:17], v[36:39], v[88:91], v[2:17]
	v_mfma_f32_32x32x16_bf16 v[2:17], v[40:43], v[92:95], v[2:17]
	ds_read_b128 v[28:31], v44 offset:18496
	ds_read_b128 v[36:39], v44 offset:18528
	s_waitcnt lgkmcnt(0)
	s_barrier
	v_mfma_f32_32x32x16_bf16 v[2:17], v[28:31], v[96:99], v[2:17]
	s_waitcnt vmcnt(0)
	v_mfma_f32_32x32x16_bf16 v[2:17], v[36:39], v[100:103], v[2:17]
	v_or_b32_e32 v24, v67, v69
	v_lshl_add_u32 v25, v68, 7, 0
	v_lshlrev_b32_e32 v26, 2, v66
	v_mul_lo_u32 v24, v24, s4
	v_add3_u32 v24, v25, v26, v24
	v_add_u32_e32 v25, 0xc800, v24
	s_nop 5
	ds_write2_b32 v25, v2, v3 offset1:132
	v_add_u32_e32 v2, 0xcc00, v24
	ds_write2_b32 v2, v4, v5 offset0:8 offset1:140
	v_add_u32_e32 v2, 0xd800, v24
	ds_write2_b32 v2, v6, v7 offset0:32 offset1:164
	v_add_u32_e32 v2, 0xdc00, v24
	ds_write2_b32 v2, v8, v9 offset0:40 offset1:172
	v_add_u32_e32 v2, 0xe800, v24
	ds_write2_b32 v2, v10, v11 offset0:64 offset1:196
	v_add_u32_e32 v2, 0xec00, v24
	ds_write2_b32 v2, v12, v13 offset0:72 offset1:204
	v_add_u32_e32 v2, 0xf800, v24
	ds_write2_b32 v2, v14, v15 offset0:96 offset1:228
	v_add_u32_e32 v2, 0xfc00, v24
	ds_write2_b32 v2, v16, v17 offset0:104 offset1:236
	v_or_b32_e32 v2, s0, v21
	v_lshlrev_b32_e32 v2, 1, v2
	v_mov_b32_e32 v3, v1
	v_lshl_add_u64 v[2:3], v[22:23], 0, v[2:3]
	s_waitcnt lgkmcnt(0)
	s_barrier
; #define LAS __attribute__((address_space(3)))
; __device__ __forceinline__ float siluf(float x) { return x * __builtin_amdgcn_rcpf(1.f + __expf(-x)); }
; __device__ __forceinline__ void r3_item(const Args& a, int L, int item, LAS unsigned char* lds) {
;     ...
;     { const int row = tid >> 3, seg = tid & 7; const LAS float* op = (const LAS float*)(lds + L_OL) + row * OLP + seg * 16; float ov[16]; float s = 0.f;
; #pragma unroll
;         for (int e = 0; e < 16; ++e) { ov[e] = op[e]; s += ov[e] * ov[e]; }
;         s += __shfl_xor(s, 1); s += __shfl_xor(s, 2); s += __shfl_xor(s, 4);
;         const float rs = rsqrtf(s * (1.0f / 128.0f) + EPS);
;         const int gcol = (hl < 4 ? GR + hl * 128 : RG + (hl - 4) * 128) + seg * 16;
;         const bf16_t* gp = proj + (R0 + row) * LD + gcol; const u32x4 g0 = *(const u32x4*)gp, g1 = *(const u32x4*)(gp + 8);
;         float gt[16] = {bflo(g0.x), bfhi(g0.x), bflo(g0.y), bfhi(g0.y), bflo(g0.z), bfhi(g0.z), bflo(g0.w), bfhi(g0.w), bflo(g1.x), bfhi(g1.x), bflo(g1.y), bfhi(g1.y), bflo(g1.z), bfhi(g1.z), bflo(g1.w), bfhi(g1.w)};
;         const float* hg = a.head_gain + (size_t)L * D + 1024 + hl * 128 + seg * 16;
;         float res[16];
; #pragma unroll
;         for (int e = 0; e < 16; ++e) res[e] = ov[e] * rs * hg[e] * siluf(gt[e]);
	global_load_dwordx4 v[22:25], v[2:3], off
	s_lshl_b32 s0, s28, 9
	s_add_u32 s0, s12, s0
	v_mul_lo_u32 v4, v20, s4
	v_lshlrev_b32_e32 v20, 2, v21
	s_addc_u32 s1, s13, 0
	v_mov_b32_e32 v21, v1
	v_add3_u32 v4, 0, v4, v20
	v_lshl_add_u64 v[38:39], s[0:1], 0, v[20:21]
	ds_read_b128 v[14:17], v4 offset:51200
	ds_read_b128 v[10:13], v4 offset:51216
	global_load_dwordx4 v[26:29], v[2:3], off offset:16
	ds_read_b128 v[6:9], v4 offset:51232
	ds_read_b128 v[2:5], v4 offset:51248
	global_load_dwordx4 v[30:33], v[38:39], off
	s_waitcnt lgkmcnt(0)
	v_mul_f32_e32 v34, v15, v15
	v_fmac_f32_e32 v34, v14, v14
	v_fmac_f32_e32 v34, v16, v16
	v_fmac_f32_e32 v34, v17, v17
	v_fmac_f32_e32 v34, v10, v10
	v_fmac_f32_e32 v34, v11, v11
	v_fmac_f32_e32 v34, v12, v12
	v_fmac_f32_e32 v34, v13, v13
	v_pk_mul_f32 v[20:21], v[6:7], v[6:7]
	s_lshl_b32 s24, s28, 8
	v_add_f32_e32 v20, v34, v20
	v_add_f32_e32 v34, v20, v21
	v_pk_mul_f32 v[20:21], v[8:9], v[8:9]
	s_mov_b64 s[0:1], 0x21300800
	v_add_f32_e32 v20, v34, v20
	v_add_f32_e32 v34, v20, v21
	v_pk_mul_f32 v[20:21], v[2:3], v[2:3]
	s_add_i32 s15, s15, s87
	v_add_f32_e32 v20, v34, v20
	v_add_f32_e32 v34, v20, v21
	v_pk_mul_f32 v[20:21], v[4:5], v[4:5]
	s_add_i32 s14, s14, s87
	v_add_f32_e32 v20, v34, v20
	v_and_b32_e32 v34, 64, v208
	v_add_f32_e32 v20, v20, v21
	v_xor_b32_e32 v21, 1, v208
	v_add_u32_e32 v40, 64, v34
	v_cmp_lt_i32_e32 vcc, v21, v40
	global_load_dwordx4 v[34:37], v[38:39], off offset:16
	s_cmpk_gt_i32 s15, 0x3ff
	v_cndmask_b32_e32 v21, v208, v21, vcc
	v_lshlrev_b32_e32 v21, 2, v21
	ds_bpermute_b32 v21, v21, v20
	s_waitcnt lgkmcnt(0)
	v_add_f32_e32 v20, v20, v21
	v_xor_b32_e32 v21, 2, v208
	v_cmp_lt_i32_e32 vcc, v21, v40
	s_waitcnt vmcnt(0)
	v_and_b32_e32 v42, 0xffff0000, v22
	v_cndmask_b32_e32 v21, v208, v21, vcc
	v_lshlrev_b32_e32 v21, 2, v21
	ds_bpermute_b32 v21, v21, v20
	v_lshlrev_b32_e32 v44, 16, v23
	v_and_b32_e32 v46, 0xffff0000, v23
	v_lshlrev_b32_e32 v48, 16, v24
	v_and_b32_e32 v50, 0xffff0000, v24
	s_waitcnt lgkmcnt(0)
	v_add_f32_e32 v20, v20, v21
	v_xor_b32_e32 v21, 4, v208
	v_cmp_lt_i32_e32 vcc, v21, v40
	v_lshlrev_b32_e32 v40, 16, v22
	v_mul_f32_e32 v24, 0xbfb8aa3b, v40
	v_cndmask_b32_e32 v21, v208, v21, vcc
	v_lshlrev_b32_e32 v21, 2, v21
	ds_bpermute_b32 v21, v21, v20
	v_exp_f32_e32 v24, v24
	v_lshlrev_b32_e32 v52, 16, v25
	v_and_b32_e32 v54, 0xffff0000, v25
	v_mov_b32_e32 v25, v30
	s_waitcnt lgkmcnt(0)
; __device__ __forceinline__ unsigned cvt_pk_bf16(float lo, float hi) { unsigned r; asm volatile("v_cvt_pk_bf16_f32 %0, %1, %2" : "=v"(r) : "v"(lo), "v"(hi)); return r; }
; __device__ __forceinline__ float siluf(float x) { return x * __builtin_amdgcn_rcpf(1.f + __expf(-x)); }
; __device__ __forceinline__ void r3_item(const Args& a, int L, int item, LAS unsigned char* lds) {
;     ...
;         const float rs = rsqrtf(s * (1.0f / 128.0f) + EPS);
;         const int gcol = (hl < 4 ? GR + hl * 128 : RG + (hl - 4) * 128) + seg * 16;
;         const bf16_t* gp = proj + (R0 + row) * LD + gcol; const u32x4 g0 = *(const u32x4*)gp, g1 = *(const u32x4*)(gp + 8);
;         float gt[16] = {bflo(g0.x), bfhi(g0.x), bflo(g0.y), bfhi(g0.y), bflo(g0.z), bfhi(g0.z), bflo(g0.w), bfhi(g0.w), bflo(g1.x), bfhi(g1.x), bflo(g1.y), bfhi(g1.y), bflo(g1.z), bfhi(g1.z), bflo(g1.w), bfhi(g1.w)};
;         const float* hg = a.head_gain + (size_t)L * D + 1024 + hl * 128 + seg * 16;
;         float res[16];
; #pragma unroll
;         for (int e = 0; e < 16; ++e) res[e] = ov[e] * rs * hg[e] * siluf(gt[e]);
;         bf16_t* mp = (bf16_t*)(a.ws + WS_MRG) + (R0 + row) * D + 1024 + hl * 128 + seg * 16;
;         u32x4 w0, w1; w0.x = cvt_pk_bf16(res[0], res[1]); w0.y = cvt_pk_bf16(res[2], res[3]); w0.z = cvt_pk_bf16(res[4], res[5]); w0.w = cvt_pk_bf16(res[6], res[7]);
;         w1.x = cvt_pk_bf16(res[8], res[9]); w1.y = cvt_pk_bf16(res[10], res[11]); w1.z = cvt_pk_bf16(res[12], res[13]); w1.w = cvt_pk_bf16(res[14], res[15]);
;         *(u32x4*)mp = w0; *(u32x4*)(mp + 8) = w1; }
	v_add_f32_e32 v20, v20, v21
	v_fmamk_f32 v20, v20, 0x3c000000, v207
	v_mul_f32_e32 v21, 0x4b800000, v20
	v_cmp_gt_f32_e32 vcc, s34, v20
	v_lshlrev_b32_e32 v56, 16, v26
	v_and_b32_e32 v58, 0xffff0000, v26
	v_cndmask_b32_e32 v20, v20, v21, vcc
	v_rsq_f32_e32 v20, v20
	v_lshlrev_b32_e32 v60, 16, v27
	v_and_b32_e32 v62, 0xffff0000, v27
	v_lshlrev_b32_e32 v64, 16, v28
	v_mul_f32_e32 v21, 0x45800000, v20
	v_cndmask_b32_e32 v69, v20, v21, vcc
	global_load_dwordx4 v[20:23], v[38:39], off offset:32
	v_mul_f32_e32 v41, v14, v69
	v_add_f32_e32 v14, 1.0, v24
	v_rcp_f32_e32 v24, v14
	v_mul_f32_e32 v14, 0xbfb8aa3b, v42
	v_exp_f32_e32 v14, v14
	v_mul_f32_e32 v43, v15, v69
	v_pk_mul_f32 v[24:25], v[24:25], v[40:41]
	v_mul_f32_e32 v45, v16, v69
	v_add_f32_e32 v14, 1.0, v14
	v_rcp_f32_e32 v30, v14
	v_mul_f32_e32 v14, 0xbfb8aa3b, v44
	v_mul_f32_e32 v40, v24, v25
	v_exp_f32_e32 v24, v14
	v_pk_mul_f32 v[14:15], v[30:31], v[42:43]
	v_mul_f32_e32 v47, v17, v69
	v_mul_f32_e32 v30, v14, v15
	v_add_f32_e32 v14, 1.0, v24
	global_load_dwordx4 v[24:27], v[38:39], off offset:48
	v_rcp_f32_e32 v14, v14
	v_mul_f32_e32 v15, 0xbfb8aa3b, v46
	v_exp_f32_e32 v16, v15
	v_mov_b32_e32 v15, v32
	v_pk_mul_f32 v[14:15], v[14:15], v[44:45]
	v_mul_f32_e32 v49, v10, v69
	v_mul_f32_e32 v31, v14, v15
	v_add_f32_e32 v14, 1.0, v16
	v_rcp_f32_e32 v32, v14
	v_mul_f32_e32 v14, 0xbfb8aa3b, v48
	v_exp_f32_e32 v16, v14
	v_mul_f32_e32 v51, v11, v69
	v_pk_mul_f32 v[14:15], v[32:33], v[46:47]
	v_mul_f32_e32 v53, v12, v69
	v_add_f32_e32 v10, 1.0, v16
	v_mul_f32_e32 v17, v14, v15
	v_rcp_f32_e32 v14, v10
	v_mul_f32_e32 v10, 0xbfb8aa3b, v50
	v_exp_f32_e32 v10, v10
	v_mov_b32_e32 v15, v34
	v_pk_mul_f32 v[14:15], v[14:15], v[48:49]
	v_mul_f32_e32 v12, 0xbfb8aa3b, v54
	v_add_f32_e32 v10, 1.0, v10
	v_rcp_f32_e32 v34, v10
	v_mul_f32_e32 v10, 0xbfb8aa3b, v52
	v_mul_f32_e32 v14, v14, v15
	v_exp_f32_e32 v15, v10
	v_pk_mul_f32 v[10:11], v[34:35], v[50:51]
	v_exp_f32_e32 v12, v12
	v_mul_f32_e32 v16, v10, v11
	v_add_f32_e32 v10, 1.0, v15
	v_rcp_f32_e32 v10, v10
	v_mov_b32_e32 v11, v36
	v_mov_b32_e32 v55, v37
	v_mul_f32_e32 v7, v7, v69
	v_pk_mul_f32 v[10:11], v[10:11], v[52:53]
	v_and_b32_e32 v28, 0xffff0000, v28
	v_mul_f32_e32 v15, v10, v11
	v_add_f32_e32 v10, 1.0, v12
	v_rcp_f32_e32 v10, v10
	v_mul_f32_e32 v12, 0xbfb8aa3b, v56
	v_exp_f32_e32 v12, v12
	v_mul_f32_e32 v11, v13, v69
	v_pk_mul_f32 v[10:11], v[10:11], v[54:55]
	v_lshlrev_b32_e32 v66, 16, v29
	v_mul_f32_e32 v32, v10, v11
	v_mul_f32_e32 v11, v6, v69
	v_add_f32_e32 v6, 1.0, v12
	v_rcp_f32_e32 v10, v6
	v_mul_f32_e32 v6, 0xbfb8aa3b, v58
	v_exp_f32_e32 v6, v6
	v_and_b32_e32 v68, 0xffff0000, v29
	v_mul_f32_e32 v3, v3, v69
	v_mul_f32_e32 v5, v5, v69
	v_add_f32_e32 v6, 1.0, v6
	v_rcp_f32_e32 v6, v6
	s_waitcnt vmcnt(0) lgkmcnt(0)
	v_mov_b32_e32 v57, v20
	v_pk_mul_f32 v[10:11], v[10:11], v[56:57]
	v_mov_b32_e32 v59, v21
	v_mul_f32_e32 v20, v10, v11
	v_mul_f32_e32 v10, 0xbfb8aa3b, v60
	v_exp_f32_e32 v10, v10
	v_pk_mul_f32 v[6:7], v[6:7], v[58:59]
	v_mov_b32_e32 v61, v22
	v_mul_f32_e32 v21, v6, v7
	v_add_f32_e32 v6, 1.0, v10
	v_mul_f32_e32 v7, v8, v69
	v_rcp_f32_e32 v6, v6
	v_mul_f32_e32 v8, 0xbfb8aa3b, v62
	v_exp_f32_e32 v8, v8
	v_mov_b32_e32 v63, v23
	v_pk_mul_f32 v[6:7], v[6:7], v[60:61]
	v_mov_b32_e32 v65, v24
	v_mul_f32_e32 v22, v6, v7
	v_add_f32_e32 v6, 1.0, v8
	v_rcp_f32_e32 v6, v6
	v_mul_f32_e32 v8, 0xbfb8aa3b, v64
	v_exp_f32_e32 v8, v8
	v_mul_f32_e32 v7, v9, v69
	v_pk_mul_f32 v[6:7], v[6:7], v[62:63]
	v_mov_b32_e32 v29, v25
	v_mul_f32_e32 v9, v6, v7
	v_mul_f32_e32 v7, v2, v69
	v_add_f32_e32 v2, 1.0, v8
	v_rcp_f32_e32 v6, v2
	v_mul_f32_e32 v2, 0xbfb8aa3b, v28
	v_exp_f32_e32 v2, v2
	v_mov_b32_e32 v67, v26
	v_pk_mul_f32 v[6:7], v[6:7], v[64:65]
	v_add_f32_e32 v2, 1.0, v2
	v_rcp_f32_e32 v2, v2
	v_mul_f32_e32 v8, v6, v7
	v_mul_f32_e32 v6, 0xbfb8aa3b, v66
	v_exp_f32_e32 v6, v6
	v_pk_mul_f32 v[2:3], v[2:3], v[28:29]
	s_nop 0
	v_mul_f32_e32 v23, v2, v3
	v_mul_f32_e32 v3, 0xbfb8aa3b, v68
	v_add_f32_e32 v2, 1.0, v6
	v_exp_f32_e32 v6, v3
	v_rcp_f32_e32 v2, v2
	v_mul_f32_e32 v3, v4, v69
	v_mov_b32_e32 v69, v27
	v_add_f32_e32 v4, 1.0, v6
	v_rcp_f32_e32 v4, v4
	v_pk_mul_f32 v[2:3], v[2:3], v[66:67]
	s_nop 0
	v_mul_f32_e32 v24, v2, v3
	v_pk_mul_f32 v[2:3], v[4:5], v[68:69]
	s_nop 0
	v_mul_f32_e32 v25, v2, v3
	v_lshlrev_b64 v[2:3], 12, v[18:19]
	v_lshl_add_u64 v[2:3], s[98:99], 0, v[2:3]
	v_lshl_add_u64 v[2:3], v[2:3], 0, s[24:25]
	v_lshl_add_u64 v[10:11], v[2:3], 0, v[0:1]
	v_lshl_add_u64 v[12:13], v[10:11], 0, s[0:1]
	v_add_co_u32_e32 v10, vcc, 0x21300000, v10
	v_cvt_pk_bf16_f32 v2, v40, v30
	v_cvt_pk_bf16_f32 v3, v31, v17
	v_cvt_pk_bf16_f32 v4, v14, v16
	v_cvt_pk_bf16_f32 v5, v15, v32
	s_nop 1
	v_addc_co_u32_e32 v11, vcc, 0, v11, vcc
	v_cvt_pk_bf16_f32 v6, v20, v21
	v_cvt_pk_bf16_f32 v7, v22, v9
	v_cvt_pk_bf16_f32 v8, v8, v23
	v_cvt_pk_bf16_f32 v9, v24, v25
	global_store_dwordx4 v[10:11], v[2:5], off offset:2048
	global_store_dwordx4 v[12:13], v[6:9], off offset:16
	s_cbranch_scc1 .LBB0_144
